# per-chunk log-forget sums (fsum) computed in the in-proj GEMM epilogue of the gate-column tile; separate foxsum pass removed
# baseline (speedup 1.0000x reference)
.LBB0_106:
	s_mov_b32 s28, s24
	s_mov_b32 s29, s25
	v_mov_b32_e32 v152, 0
	v_mov_b32_e32 v153, 0
	s_cmp_eq_u32 s25, 0x600
	s_cbranch_scc0 .Lglf_init_done
	v_readfirstlane_b32 s6, v238
	s_nop 1
	s_cmp_eq_u32 s6, 0
	s_cbranch_scc1 .Lglf_init_own
	s_movk_i32 s29, 0x601
	s_branch .Lglf_init_done
.Lglf_init_own:
	v_readlane_b32 s0, v245, 10
	v_readlane_b32 s1, v245, 11
	v_readlane_b32 s6, v245, 61
	s_nop 1
	s_lshl_b32 s6, s6, 5
	s_add_u32 s0, s0, s6
	s_addc_u32 s1, s1, 0
	v_mov_b32_e32 v144, 0
	global_load_dwordx4 v[170:173], v144, s[0:1]
	global_load_dwordx4 v[148:151], v144, s[0:1] offset:16
	v_readfirstlane_b32 s6, v239
	s_nop 1
	s_add_u32 s6, s6, s24
	s_mov_b32 s7, 0
	s_cmp_ge_u32 s6, 0x2080
	s_addc_u32 s7, s7, 0
	s_cmp_ge_u32 s6, 0x4100
	s_addc_u32 s7, s7, 0
	s_cmp_ge_u32 s6, 0x6180
	s_addc_u32 s7, s7, 0
	s_mul_i32 s7, s7, 0x2080
	s_sub_u32 s6, s6, s7
	v_and_b32_e32 v147, 7, v239
	v_add_u32_e32 v147, s6, v147
	v_mov_b32_e32 v154, 0
	v_mov_b32_e32 v155, 0
	v_mov_b32_e32 v156, 0
	v_mov_b32_e32 v157, 0
	v_mov_b32_e32 v158, 0
	v_mov_b32_e32 v159, 0
	v_mov_b32_e32 v160, 0
	v_mov_b32_e32 v161, 0
	v_mov_b32_e32 v162, 0
	v_mov_b32_e32 v163, 0
	v_mov_b32_e32 v164, 0
	v_mov_b32_e32 v165, 0
	v_mov_b32_e32 v166, 0
	v_mov_b32_e32 v167, 0
	v_mov_b32_e32 v168, 0
	v_mov_b32_e32 v169, 0
.Lglf_init_done:
	v_add_u32_e32 v140, s25, v238
	v_ashrrev_i32_e32 v141, 31, v140
	s_movk_i32 s0, 0x1618
	v_or_b32_e32 v138, s24, v239
	v_lshl_add_u64 v[136:137], v[140:141], 1, s[56:57]
	v_cmp_gt_i32_e64 s[0:1], s0, v140
	v_cvt_pk_bf16_f32 v140, v112, v113
	v_cvt_pk_bf16_f32 v141, v114, v115
	v_cvt_pk_bf16_f32 v114, v116, v117
	v_cvt_pk_bf16_f32 v115, v118, v119
	v_add_u32_e32 v112, 0xc000, v240
	v_cvt_pk_bf16_f32 v96, v96, v97
	v_cvt_pk_bf16_f32 v97, v98, v99
	v_cvt_pk_bf16_f32 v98, v100, v101
	v_cvt_pk_bf16_f32 v99, v102, v103
	s_waitcnt vmcnt(0)
	ds_write2_b64 v112, v[140:141], v[114:115] offset1:2
	v_cvt_pk_bf16_f32 v114, v120, v121
	v_cvt_pk_bf16_f32 v115, v122, v123
	v_cvt_pk_bf16_f32 v116, v124, v125
	v_cvt_pk_bf16_f32 v117, v126, v127
	ds_write2_b64 v112, v[114:115], v[116:117] offset0:4 offset1:6
	ds_write2_b64 v112, v[96:97], v[98:99] offset0:8 offset1:10
	v_cvt_pk_bf16_f32 v96, v104, v105
	v_cvt_pk_bf16_f32 v97, v106, v107
	v_cvt_pk_bf16_f32 v98, v108, v109
	v_cvt_pk_bf16_f32 v99, v110, v111
	ds_write2_b64 v112, v[96:97], v[98:99] offset0:12 offset1:14
	s_and_saveexec_b64 s[6:7], s[0:1]
	s_cbranch_execz .LBB0_108
	ds_read_b128 v[96:99], v241 offset:49152
	v_mad_i64_i32 v[100:101], s[24:25], v138, s13, v[136:137]
	v_add_co_u32_e32 v102, vcc, 0x16000, v100
	s_waitcnt lgkmcnt(0)
	s_cmp_lt_u32 s29, 0x400
	s_cbranch_scc0 .Lgn_s0
	v_lshlrev_b32_e32 v144, 16, v96
	v_and_b32_e32 v145, 0xffff0000, v96
	v_mul_f32_e32 v146, v144, v144
	v_fmac_f32_e32 v146, v145, v145
	v_lshlrev_b32_e32 v144, 16, v97
	v_and_b32_e32 v145, 0xffff0000, v97
	v_fmac_f32_e32 v146, v144, v144
	v_fmac_f32_e32 v146, v145, v145
	v_lshlrev_b32_e32 v144, 16, v98
	v_and_b32_e32 v145, 0xffff0000, v98
	v_fmac_f32_e32 v146, v144, v144
	v_fmac_f32_e32 v146, v145, v145
	v_lshlrev_b32_e32 v144, 16, v99
	v_and_b32_e32 v145, 0xffff0000, v99
	v_fmac_f32_e32 v146, v144, v144
	v_fmac_f32_e32 v146, v145, v145
	s_nop 1
	v_add_f32_dpp v146, v146, v146 quad_perm:[1,0,3,2] row_mask:0xf bank_mask:0xf
	s_nop 1
	v_add_f32_dpp v146, v146, v146 quad_perm:[2,3,0,1] row_mask:0xf bank_mask:0xf
	s_nop 1
	v_add_f32_dpp v146, v146, v146 row_half_mirror row_mask:0xf bank_mask:0xf
	s_nop 0
	v_max_f32_e32 v152, v152, v146
.Lgn_s0:
	s_cmp_eq_u32 s29, 0x600
	s_cbranch_scc0 .Lglf_s0
	v_add_u32_e32 v146, 0, v147
	v_cmp_le_u32_e64 s[24:25], s36, v146
	v_lshlrev_b32_e32 v144, 16, v96
	v_add_f32_e32 v144, v170, v144
	v_mul_f32_e64 v145, |v144|, s98
	v_exp_f32_e32 v145, v145
	v_min_f32_e32 v144, 0, v144
	v_add_f32_e32 v145, 1.0, v145
	v_log_f32_e32 v145, v145
	s_nop 0
	v_fmac_f32_e32 v144, 0xbf317218, v145
	v_cndmask_b32_e64 v144, 0, v144, s[24:25]
	v_add_f32_e32 v154, v154, v144
	v_and_b32_e32 v144, 0xffff0000, v96
	v_add_f32_e32 v144, v171, v144
	v_mul_f32_e64 v145, |v144|, s98
	v_exp_f32_e32 v145, v145
	v_min_f32_e32 v144, 0, v144
	v_add_f32_e32 v145, 1.0, v145
	v_log_f32_e32 v145, v145
	s_nop 0
	v_fmac_f32_e32 v144, 0xbf317218, v145
	v_cndmask_b32_e64 v144, 0, v144, s[24:25]
	v_add_f32_e32 v155, v155, v144
	v_lshlrev_b32_e32 v144, 16, v97
	v_add_f32_e32 v144, v172, v144
	v_mul_f32_e64 v145, |v144|, s98
	v_exp_f32_e32 v145, v145
	v_min_f32_e32 v144, 0, v144
	v_add_f32_e32 v145, 1.0, v145
	v_log_f32_e32 v145, v145
	s_nop 0
	v_fmac_f32_e32 v144, 0xbf317218, v145
	v_cndmask_b32_e64 v144, 0, v144, s[24:25]
	v_add_f32_e32 v156, v156, v144
	v_and_b32_e32 v144, 0xffff0000, v97
	v_add_f32_e32 v144, v173, v144
	v_mul_f32_e64 v145, |v144|, s98
	v_exp_f32_e32 v145, v145
	v_min_f32_e32 v144, 0, v144
	v_add_f32_e32 v145, 1.0, v145
	v_log_f32_e32 v145, v145
	s_nop 0
	v_fmac_f32_e32 v144, 0xbf317218, v145
	v_cndmask_b32_e64 v144, 0, v144, s[24:25]
	v_add_f32_e32 v157, v157, v144
	v_lshlrev_b32_e32 v144, 16, v98
	v_add_f32_e32 v144, v148, v144
	v_mul_f32_e64 v145, |v144|, s98
	v_exp_f32_e32 v145, v145
	v_min_f32_e32 v144, 0, v144
	v_add_f32_e32 v145, 1.0, v145
	v_log_f32_e32 v145, v145
	s_nop 0
	v_fmac_f32_e32 v144, 0xbf317218, v145
	v_cndmask_b32_e64 v144, 0, v144, s[24:25]
	v_add_f32_e32 v158, v158, v144
	v_and_b32_e32 v144, 0xffff0000, v98
	v_add_f32_e32 v144, v149, v144
	v_mul_f32_e64 v145, |v144|, s98
	v_exp_f32_e32 v145, v145
	v_min_f32_e32 v144, 0, v144
	v_add_f32_e32 v145, 1.0, v145
	v_log_f32_e32 v145, v145
	s_nop 0
	v_fmac_f32_e32 v144, 0xbf317218, v145
	v_cndmask_b32_e64 v144, 0, v144, s[24:25]
	v_add_f32_e32 v159, v159, v144
	v_lshlrev_b32_e32 v144, 16, v99
	v_add_f32_e32 v144, v150, v144
	v_mul_f32_e64 v145, |v144|, s98
	v_exp_f32_e32 v145, v145
	v_min_f32_e32 v144, 0, v144
	v_add_f32_e32 v145, 1.0, v145
	v_log_f32_e32 v145, v145
	s_nop 0
	v_fmac_f32_e32 v144, 0xbf317218, v145
	v_cndmask_b32_e64 v144, 0, v144, s[24:25]
	v_add_f32_e32 v160, v160, v144
	v_and_b32_e32 v144, 0xffff0000, v99
	v_add_f32_e32 v144, v151, v144
	v_mul_f32_e64 v145, |v144|, s98
	v_exp_f32_e32 v145, v145
	v_min_f32_e32 v144, 0, v144
	v_add_f32_e32 v145, 1.0, v145
	v_log_f32_e32 v145, v145
	s_nop 0
	v_fmac_f32_e32 v144, 0xbf317218, v145
	v_cndmask_b32_e64 v144, 0, v144, s[24:25]
	v_add_f32_e32 v161, v161, v144

.Lgn_s1:
	s_cmp_eq_u32 s29, 0x600
	s_cbranch_scc0 .Lglf_s1
	v_add_u32_e32 v146, 8, v147
	v_cmp_le_u32_e64 s[24:25], s36, v146
	v_lshlrev_b32_e32 v144, 16, v96
	v_add_f32_e32 v144, v170, v144
	v_mul_f32_e64 v145, |v144|, s98
	v_exp_f32_e32 v145, v145
	v_min_f32_e32 v144, 0, v144
	v_add_f32_e32 v145, 1.0, v145
	v_log_f32_e32 v145, v145
	s_nop 0
	v_fmac_f32_e32 v144, 0xbf317218, v145
	v_cndmask_b32_e64 v144, 0, v144, s[24:25]
	v_add_f32_e32 v154, v154, v144
	v_and_b32_e32 v144, 0xffff0000, v96
	v_add_f32_e32 v144, v171, v144
	v_mul_f32_e64 v145, |v144|, s98
	v_exp_f32_e32 v145, v145
	v_min_f32_e32 v144, 0, v144
	v_add_f32_e32 v145, 1.0, v145
	v_log_f32_e32 v145, v145
	s_nop 0
	v_fmac_f32_e32 v144, 0xbf317218, v145
	v_cndmask_b32_e64 v144, 0, v144, s[24:25]
	v_add_f32_e32 v155, v155, v144
	v_lshlrev_b32_e32 v144, 16, v97
	v_add_f32_e32 v144, v172, v144
	v_mul_f32_e64 v145, |v144|, s98
	v_exp_f32_e32 v145, v145
	v_min_f32_e32 v144, 0, v144
	v_add_f32_e32 v145, 1.0, v145
	v_log_f32_e32 v145, v145
	s_nop 0
	v_fmac_f32_e32 v144, 0xbf317218, v145
	v_cndmask_b32_e64 v144, 0, v144, s[24:25]
	v_add_f32_e32 v156, v156, v144
	v_and_b32_e32 v144, 0xffff0000, v97
	v_add_f32_e32 v144, v173, v144
	v_mul_f32_e64 v145, |v144|, s98
	v_exp_f32_e32 v145, v145
	v_min_f32_e32 v144, 0, v144
	v_add_f32_e32 v145, 1.0, v145
	v_log_f32_e32 v145, v145
	s_nop 0
	v_fmac_f32_e32 v144, 0xbf317218, v145
	v_cndmask_b32_e64 v144, 0, v144, s[24:25]
	v_add_f32_e32 v157, v157, v144
	v_lshlrev_b32_e32 v144, 16, v98
	v_add_f32_e32 v144, v148, v144
	v_mul_f32_e64 v145, |v144|, s98
	v_exp_f32_e32 v145, v145
	v_min_f32_e32 v144, 0, v144
	v_add_f32_e32 v145, 1.0, v145
	v_log_f32_e32 v145, v145
	s_nop 0
	v_fmac_f32_e32 v144, 0xbf317218, v145
	v_cndmask_b32_e64 v144, 0, v144, s[24:25]
	v_add_f32_e32 v158, v158, v144
	v_and_b32_e32 v144, 0xffff0000, v98
	v_add_f32_e32 v144, v149, v144
	v_mul_f32_e64 v145, |v144|, s98
	v_exp_f32_e32 v145, v145
	v_min_f32_e32 v144, 0, v144
	v_add_f32_e32 v145, 1.0, v145
	v_log_f32_e32 v145, v145
	s_nop 0
	v_fmac_f32_e32 v144, 0xbf317218, v145
	v_cndmask_b32_e64 v144, 0, v144, s[24:25]
	v_add_f32_e32 v159, v159, v144
	v_lshlrev_b32_e32 v144, 16, v99
	v_add_f32_e32 v144, v150, v144
	v_mul_f32_e64 v145, |v144|, s98
	v_exp_f32_e32 v145, v145
	v_min_f32_e32 v144, 0, v144
	v_add_f32_e32 v145, 1.0, v145
	v_log_f32_e32 v145, v145
	s_nop 0
	v_fmac_f32_e32 v144, 0xbf317218, v145
	v_cndmask_b32_e64 v144, 0, v144, s[24:25]
	v_add_f32_e32 v160, v160, v144
	v_and_b32_e32 v144, 0xffff0000, v99
	v_add_f32_e32 v144, v151, v144
	v_mul_f32_e64 v145, |v144|, s98
	v_exp_f32_e32 v145, v145
	v_min_f32_e32 v144, 0, v144
	v_add_f32_e32 v145, 1.0, v145
	v_log_f32_e32 v145, v145
	s_nop 0
	v_fmac_f32_e32 v144, 0xbf317218, v145
	v_cndmask_b32_e64 v144, 0, v144, s[24:25]
	v_add_f32_e32 v161, v161, v144

.Lgn_s2:
	s_cmp_eq_u32 s29, 0x600
	s_cbranch_scc0 .Lglf_s2
	v_add_u32_e32 v146, 16, v147
	v_cmp_le_u32_e64 s[24:25], s36, v146
	v_lshlrev_b32_e32 v144, 16, v96
	v_add_f32_e32 v144, v170, v144
	v_mul_f32_e64 v145, |v144|, s98
	v_exp_f32_e32 v145, v145
	v_min_f32_e32 v144, 0, v144
	v_add_f32_e32 v145, 1.0, v145
	v_log_f32_e32 v145, v145
	s_nop 0
	v_fmac_f32_e32 v144, 0xbf317218, v145
	v_cndmask_b32_e64 v144, 0, v144, s[24:25]
	v_add_f32_e32 v154, v154, v144
	v_and_b32_e32 v144, 0xffff0000, v96
	v_add_f32_e32 v144, v171, v144
	v_mul_f32_e64 v145, |v144|, s98
	v_exp_f32_e32 v145, v145
	v_min_f32_e32 v144, 0, v144
	v_add_f32_e32 v145, 1.0, v145
	v_log_f32_e32 v145, v145
	s_nop 0
	v_fmac_f32_e32 v144, 0xbf317218, v145
	v_cndmask_b32_e64 v144, 0, v144, s[24:25]
	v_add_f32_e32 v155, v155, v144
	v_lshlrev_b32_e32 v144, 16, v97
	v_add_f32_e32 v144, v172, v144
	v_mul_f32_e64 v145, |v144|, s98
	v_exp_f32_e32 v145, v145
	v_min_f32_e32 v144, 0, v144
	v_add_f32_e32 v145, 1.0, v145
	v_log_f32_e32 v145, v145
	s_nop 0
	v_fmac_f32_e32 v144, 0xbf317218, v145
	v_cndmask_b32_e64 v144, 0, v144, s[24:25]
	v_add_f32_e32 v156, v156, v144
	v_and_b32_e32 v144, 0xffff0000, v97
	v_add_f32_e32 v144, v173, v144
	v_mul_f32_e64 v145, |v144|, s98
	v_exp_f32_e32 v145, v145
	v_min_f32_e32 v144, 0, v144
	v_add_f32_e32 v145, 1.0, v145
	v_log_f32_e32 v145, v145
	s_nop 0
	v_fmac_f32_e32 v144, 0xbf317218, v145
	v_cndmask_b32_e64 v144, 0, v144, s[24:25]
	v_add_f32_e32 v157, v157, v144
	v_lshlrev_b32_e32 v144, 16, v98
	v_add_f32_e32 v144, v148, v144
	v_mul_f32_e64 v145, |v144|, s98
	v_exp_f32_e32 v145, v145
	v_min_f32_e32 v144, 0, v144
	v_add_f32_e32 v145, 1.0, v145
	v_log_f32_e32 v145, v145
	s_nop 0
	v_fmac_f32_e32 v144, 0xbf317218, v145
	v_cndmask_b32_e64 v144, 0, v144, s[24:25]
	v_add_f32_e32 v158, v158, v144
	v_and_b32_e32 v144, 0xffff0000, v98
	v_add_f32_e32 v144, v149, v144
	v_mul_f32_e64 v145, |v144|, s98
	v_exp_f32_e32 v145, v145
	v_min_f32_e32 v144, 0, v144
	v_add_f32_e32 v145, 1.0, v145
	v_log_f32_e32 v145, v145
	s_nop 0
	v_fmac_f32_e32 v144, 0xbf317218, v145
	v_cndmask_b32_e64 v144, 0, v144, s[24:25]
	v_add_f32_e32 v159, v159, v144
	v_lshlrev_b32_e32 v144, 16, v99
	v_add_f32_e32 v144, v150, v144
	v_mul_f32_e64 v145, |v144|, s98
	v_exp_f32_e32 v145, v145
	v_min_f32_e32 v144, 0, v144
	v_add_f32_e32 v145, 1.0, v145
	v_log_f32_e32 v145, v145
	s_nop 0
	v_fmac_f32_e32 v144, 0xbf317218, v145
	v_cndmask_b32_e64 v144, 0, v144, s[24:25]
	v_add_f32_e32 v160, v160, v144
	v_and_b32_e32 v144, 0xffff0000, v99
	v_add_f32_e32 v144, v151, v144
	v_mul_f32_e64 v145, |v144|, s98
	v_exp_f32_e32 v145, v145
	v_min_f32_e32 v144, 0, v144
	v_add_f32_e32 v145, 1.0, v145
	v_log_f32_e32 v145, v145
	s_nop 0
	v_fmac_f32_e32 v144, 0xbf317218, v145
	v_cndmask_b32_e64 v144, 0, v144, s[24:25]
	v_add_f32_e32 v161, v161, v144

.Lgn_s3:
	s_cmp_eq_u32 s29, 0x600
	s_cbranch_scc0 .Lglf_s3
	v_add_u32_e32 v146, 24, v147
	v_cmp_le_u32_e64 s[24:25], s36, v146
	v_lshlrev_b32_e32 v144, 16, v96
	v_add_f32_e32 v144, v170, v144
	v_mul_f32_e64 v145, |v144|, s98
	v_exp_f32_e32 v145, v145
	v_min_f32_e32 v144, 0, v144
	v_add_f32_e32 v145, 1.0, v145
	v_log_f32_e32 v145, v145
	s_nop 0
	v_fmac_f32_e32 v144, 0xbf317218, v145
	v_cndmask_b32_e64 v144, 0, v144, s[24:25]
	v_add_f32_e32 v154, v154, v144
	v_and_b32_e32 v144, 0xffff0000, v96
	v_add_f32_e32 v144, v171, v144
	v_mul_f32_e64 v145, |v144|, s98
	v_exp_f32_e32 v145, v145
	v_min_f32_e32 v144, 0, v144
	v_add_f32_e32 v145, 1.0, v145
	v_log_f32_e32 v145, v145
	s_nop 0
	v_fmac_f32_e32 v144, 0xbf317218, v145
	v_cndmask_b32_e64 v144, 0, v144, s[24:25]
	v_add_f32_e32 v155, v155, v144
	v_lshlrev_b32_e32 v144, 16, v97
	v_add_f32_e32 v144, v172, v144
	v_mul_f32_e64 v145, |v144|, s98
	v_exp_f32_e32 v145, v145
	v_min_f32_e32 v144, 0, v144
	v_add_f32_e32 v145, 1.0, v145
	v_log_f32_e32 v145, v145
	s_nop 0
	v_fmac_f32_e32 v144, 0xbf317218, v145
	v_cndmask_b32_e64 v144, 0, v144, s[24:25]
	v_add_f32_e32 v156, v156, v144
	v_and_b32_e32 v144, 0xffff0000, v97
	v_add_f32_e32 v144, v173, v144
	v_mul_f32_e64 v145, |v144|, s98
	v_exp_f32_e32 v145, v145
	v_min_f32_e32 v144, 0, v144
	v_add_f32_e32 v145, 1.0, v145
	v_log_f32_e32 v145, v145
	s_nop 0
	v_fmac_f32_e32 v144, 0xbf317218, v145
	v_cndmask_b32_e64 v144, 0, v144, s[24:25]
	v_add_f32_e32 v157, v157, v144
	v_lshlrev_b32_e32 v144, 16, v98
	v_add_f32_e32 v144, v148, v144
	v_mul_f32_e64 v145, |v144|, s98
	v_exp_f32_e32 v145, v145
	v_min_f32_e32 v144, 0, v144
	v_add_f32_e32 v145, 1.0, v145
	v_log_f32_e32 v145, v145
	s_nop 0
	v_fmac_f32_e32 v144, 0xbf317218, v145
	v_cndmask_b32_e64 v144, 0, v144, s[24:25]
	v_add_f32_e32 v158, v158, v144
	v_and_b32_e32 v144, 0xffff0000, v98
	v_add_f32_e32 v144, v149, v144
	v_mul_f32_e64 v145, |v144|, s98
	v_exp_f32_e32 v145, v145
	v_min_f32_e32 v144, 0, v144
	v_add_f32_e32 v145, 1.0, v145
	v_log_f32_e32 v145, v145
	s_nop 0
	v_fmac_f32_e32 v144, 0xbf317218, v145
	v_cndmask_b32_e64 v144, 0, v144, s[24:25]
	v_add_f32_e32 v159, v159, v144
	v_lshlrev_b32_e32 v144, 16, v99
	v_add_f32_e32 v144, v150, v144
	v_mul_f32_e64 v145, |v144|, s98
	v_exp_f32_e32 v145, v145
	v_min_f32_e32 v144, 0, v144
	v_add_f32_e32 v145, 1.0, v145
	v_log_f32_e32 v145, v145
	s_nop 0
	v_fmac_f32_e32 v144, 0xbf317218, v145
	v_cndmask_b32_e64 v144, 0, v144, s[24:25]
	v_add_f32_e32 v160, v160, v144
	v_and_b32_e32 v144, 0xffff0000, v99
	v_add_f32_e32 v144, v151, v144
	v_mul_f32_e64 v145, |v144|, s98
	v_exp_f32_e32 v145, v145
	v_min_f32_e32 v144, 0, v144
	v_add_f32_e32 v145, 1.0, v145
	v_log_f32_e32 v145, v145
	s_nop 0
	v_fmac_f32_e32 v144, 0xbf317218, v145
	v_cndmask_b32_e64 v144, 0, v144, s[24:25]
	v_add_f32_e32 v161, v161, v144

.Lgn_s4:
	s_cmp_eq_u32 s29, 0x600
	s_cbranch_scc0 .Lglf_s4
	v_add_u32_e32 v146, 32, v147
	v_cmp_le_u32_e64 s[24:25], s36, v146
	v_lshlrev_b32_e32 v144, 16, v64
	v_add_f32_e32 v144, v170, v144
	v_mul_f32_e64 v145, |v144|, s98
	v_exp_f32_e32 v145, v145
	v_min_f32_e32 v144, 0, v144
	v_add_f32_e32 v145, 1.0, v145
	v_log_f32_e32 v145, v145
	s_nop 0
	v_fmac_f32_e32 v144, 0xbf317218, v145
	v_cndmask_b32_e64 v144, 0, v144, s[24:25]
	v_add_f32_e32 v154, v154, v144
	v_and_b32_e32 v144, 0xffff0000, v64
	v_add_f32_e32 v144, v171, v144
	v_mul_f32_e64 v145, |v144|, s98
	v_exp_f32_e32 v145, v145
	v_min_f32_e32 v144, 0, v144
	v_add_f32_e32 v145, 1.0, v145
	v_log_f32_e32 v145, v145
	s_nop 0
	v_fmac_f32_e32 v144, 0xbf317218, v145
	v_cndmask_b32_e64 v144, 0, v144, s[24:25]
	v_add_f32_e32 v155, v155, v144
	v_lshlrev_b32_e32 v144, 16, v65
	v_add_f32_e32 v144, v172, v144
	v_mul_f32_e64 v145, |v144|, s98
	v_exp_f32_e32 v145, v145
	v_min_f32_e32 v144, 0, v144
	v_add_f32_e32 v145, 1.0, v145
	v_log_f32_e32 v145, v145
	s_nop 0
	v_fmac_f32_e32 v144, 0xbf317218, v145
	v_cndmask_b32_e64 v144, 0, v144, s[24:25]
	v_add_f32_e32 v156, v156, v144
	v_and_b32_e32 v144, 0xffff0000, v65
	v_add_f32_e32 v144, v173, v144
	v_mul_f32_e64 v145, |v144|, s98
	v_exp_f32_e32 v145, v145
	v_min_f32_e32 v144, 0, v144
	v_add_f32_e32 v145, 1.0, v145
	v_log_f32_e32 v145, v145
	s_nop 0
	v_fmac_f32_e32 v144, 0xbf317218, v145
	v_cndmask_b32_e64 v144, 0, v144, s[24:25]
	v_add_f32_e32 v157, v157, v144
	v_lshlrev_b32_e32 v144, 16, v66
	v_add_f32_e32 v144, v148, v144
	v_mul_f32_e64 v145, |v144|, s98
	v_exp_f32_e32 v145, v145
	v_min_f32_e32 v144, 0, v144
	v_add_f32_e32 v145, 1.0, v145
	v_log_f32_e32 v145, v145
	s_nop 0
	v_fmac_f32_e32 v144, 0xbf317218, v145
	v_cndmask_b32_e64 v144, 0, v144, s[24:25]
	v_add_f32_e32 v158, v158, v144
	v_and_b32_e32 v144, 0xffff0000, v66
	v_add_f32_e32 v144, v149, v144
	v_mul_f32_e64 v145, |v144|, s98
	v_exp_f32_e32 v145, v145
	v_min_f32_e32 v144, 0, v144
	v_add_f32_e32 v145, 1.0, v145
	v_log_f32_e32 v145, v145
	s_nop 0
	v_fmac_f32_e32 v144, 0xbf317218, v145
	v_cndmask_b32_e64 v144, 0, v144, s[24:25]
	v_add_f32_e32 v159, v159, v144
	v_lshlrev_b32_e32 v144, 16, v67
	v_add_f32_e32 v144, v150, v144
	v_mul_f32_e64 v145, |v144|, s98
	v_exp_f32_e32 v145, v145
	v_min_f32_e32 v144, 0, v144
	v_add_f32_e32 v145, 1.0, v145
	v_log_f32_e32 v145, v145
	s_nop 0
	v_fmac_f32_e32 v144, 0xbf317218, v145
	v_cndmask_b32_e64 v144, 0, v144, s[24:25]
	v_add_f32_e32 v160, v160, v144
	v_and_b32_e32 v144, 0xffff0000, v67
	v_add_f32_e32 v144, v151, v144
	v_mul_f32_e64 v145, |v144|, s98
	v_exp_f32_e32 v145, v145
	v_min_f32_e32 v144, 0, v144
	v_add_f32_e32 v145, 1.0, v145
	v_log_f32_e32 v145, v145
	s_nop 0
	v_fmac_f32_e32 v144, 0xbf317218, v145
	v_cndmask_b32_e64 v144, 0, v144, s[24:25]
	v_add_f32_e32 v161, v161, v144

.Lgn_s5:
	s_cmp_eq_u32 s29, 0x600
	s_cbranch_scc0 .Lglf_s5
	v_add_u32_e32 v146, 40, v147
	v_cmp_le_u32_e64 s[24:25], s36, v146
	v_lshlrev_b32_e32 v144, 16, v64
	v_add_f32_e32 v144, v170, v144
	v_mul_f32_e64 v145, |v144|, s98
	v_exp_f32_e32 v145, v145
	v_min_f32_e32 v144, 0, v144
	v_add_f32_e32 v145, 1.0, v145
	v_log_f32_e32 v145, v145
	s_nop 0
	v_fmac_f32_e32 v144, 0xbf317218, v145
	v_cndmask_b32_e64 v144, 0, v144, s[24:25]
	v_add_f32_e32 v154, v154, v144
	v_and_b32_e32 v144, 0xffff0000, v64
	v_add_f32_e32 v144, v171, v144
	v_mul_f32_e64 v145, |v144|, s98
	v_exp_f32_e32 v145, v145
	v_min_f32_e32 v144, 0, v144
	v_add_f32_e32 v145, 1.0, v145
	v_log_f32_e32 v145, v145
	s_nop 0
	v_fmac_f32_e32 v144, 0xbf317218, v145
	v_cndmask_b32_e64 v144, 0, v144, s[24:25]
	v_add_f32_e32 v155, v155, v144
	v_lshlrev_b32_e32 v144, 16, v65
	v_add_f32_e32 v144, v172, v144
	v_mul_f32_e64 v145, |v144|, s98
	v_exp_f32_e32 v145, v145
	v_min_f32_e32 v144, 0, v144
	v_add_f32_e32 v145, 1.0, v145
	v_log_f32_e32 v145, v145
	s_nop 0
	v_fmac_f32_e32 v144, 0xbf317218, v145
	v_cndmask_b32_e64 v144, 0, v144, s[24:25]
	v_add_f32_e32 v156, v156, v144
	v_and_b32_e32 v144, 0xffff0000, v65
	v_add_f32_e32 v144, v173, v144
	v_mul_f32_e64 v145, |v144|, s98
	v_exp_f32_e32 v145, v145
	v_min_f32_e32 v144, 0, v144
	v_add_f32_e32 v145, 1.0, v145
	v_log_f32_e32 v145, v145
	s_nop 0
	v_fmac_f32_e32 v144, 0xbf317218, v145
	v_cndmask_b32_e64 v144, 0, v144, s[24:25]
	v_add_f32_e32 v157, v157, v144
	v_lshlrev_b32_e32 v144, 16, v66
	v_add_f32_e32 v144, v148, v144
	v_mul_f32_e64 v145, |v144|, s98
	v_exp_f32_e32 v145, v145
	v_min_f32_e32 v144, 0, v144
	v_add_f32_e32 v145, 1.0, v145
	v_log_f32_e32 v145, v145
	s_nop 0
	v_fmac_f32_e32 v144, 0xbf317218, v145
	v_cndmask_b32_e64 v144, 0, v144, s[24:25]
	v_add_f32_e32 v158, v158, v144
	v_and_b32_e32 v144, 0xffff0000, v66
	v_add_f32_e32 v144, v149, v144
	v_mul_f32_e64 v145, |v144|, s98
	v_exp_f32_e32 v145, v145
	v_min_f32_e32 v144, 0, v144
	v_add_f32_e32 v145, 1.0, v145
	v_log_f32_e32 v145, v145
	s_nop 0
	v_fmac_f32_e32 v144, 0xbf317218, v145
	v_cndmask_b32_e64 v144, 0, v144, s[24:25]
	v_add_f32_e32 v159, v159, v144
	v_lshlrev_b32_e32 v144, 16, v67
	v_add_f32_e32 v144, v150, v144
	v_mul_f32_e64 v145, |v144|, s98
	v_exp_f32_e32 v145, v145
	v_min_f32_e32 v144, 0, v144
	v_add_f32_e32 v145, 1.0, v145
	v_log_f32_e32 v145, v145
	s_nop 0
	v_fmac_f32_e32 v144, 0xbf317218, v145
	v_cndmask_b32_e64 v144, 0, v144, s[24:25]
	v_add_f32_e32 v160, v160, v144
	v_and_b32_e32 v144, 0xffff0000, v67
	v_add_f32_e32 v144, v151, v144
	v_mul_f32_e64 v145, |v144|, s98
	v_exp_f32_e32 v145, v145
	v_min_f32_e32 v144, 0, v144
	v_add_f32_e32 v145, 1.0, v145
	v_log_f32_e32 v145, v145
	s_nop 0
	v_fmac_f32_e32 v144, 0xbf317218, v145
	v_cndmask_b32_e64 v144, 0, v144, s[24:25]
	v_add_f32_e32 v161, v161, v144

.Lgn_s6:
	s_cmp_eq_u32 s29, 0x600
	s_cbranch_scc0 .Lglf_s6
	v_add_u32_e32 v146, 48, v147
	v_cmp_le_u32_e64 s[24:25], s36, v146
	v_lshlrev_b32_e32 v144, 16, v64
	v_add_f32_e32 v144, v170, v144
	v_mul_f32_e64 v145, |v144|, s98
	v_exp_f32_e32 v145, v145
	v_min_f32_e32 v144, 0, v144
	v_add_f32_e32 v145, 1.0, v145
	v_log_f32_e32 v145, v145
	s_nop 0
	v_fmac_f32_e32 v144, 0xbf317218, v145
	v_cndmask_b32_e64 v144, 0, v144, s[24:25]
	v_add_f32_e32 v154, v154, v144
	v_and_b32_e32 v144, 0xffff0000, v64
	v_add_f32_e32 v144, v171, v144
	v_mul_f32_e64 v145, |v144|, s98
	v_exp_f32_e32 v145, v145
	v_min_f32_e32 v144, 0, v144
	v_add_f32_e32 v145, 1.0, v145
	v_log_f32_e32 v145, v145
	s_nop 0
	v_fmac_f32_e32 v144, 0xbf317218, v145
	v_cndmask_b32_e64 v144, 0, v144, s[24:25]
	v_add_f32_e32 v155, v155, v144
	v_lshlrev_b32_e32 v144, 16, v65
	v_add_f32_e32 v144, v172, v144
	v_mul_f32_e64 v145, |v144|, s98
	v_exp_f32_e32 v145, v145
	v_min_f32_e32 v144, 0, v144
	v_add_f32_e32 v145, 1.0, v145
	v_log_f32_e32 v145, v145
	s_nop 0
	v_fmac_f32_e32 v144, 0xbf317218, v145
	v_cndmask_b32_e64 v144, 0, v144, s[24:25]
	v_add_f32_e32 v156, v156, v144
	v_and_b32_e32 v144, 0xffff0000, v65
	v_add_f32_e32 v144, v173, v144
	v_mul_f32_e64 v145, |v144|, s98
	v_exp_f32_e32 v145, v145
	v_min_f32_e32 v144, 0, v144
	v_add_f32_e32 v145, 1.0, v145
	v_log_f32_e32 v145, v145
	s_nop 0
	v_fmac_f32_e32 v144, 0xbf317218, v145
	v_cndmask_b32_e64 v144, 0, v144, s[24:25]
	v_add_f32_e32 v157, v157, v144
	v_lshlrev_b32_e32 v144, 16, v66
	v_add_f32_e32 v144, v148, v144
	v_mul_f32_e64 v145, |v144|, s98
	v_exp_f32_e32 v145, v145
	v_min_f32_e32 v144, 0, v144
	v_add_f32_e32 v145, 1.0, v145
	v_log_f32_e32 v145, v145
	s_nop 0
	v_fmac_f32_e32 v144, 0xbf317218, v145
	v_cndmask_b32_e64 v144, 0, v144, s[24:25]
	v_add_f32_e32 v158, v158, v144
	v_and_b32_e32 v144, 0xffff0000, v66
	v_add_f32_e32 v144, v149, v144
	v_mul_f32_e64 v145, |v144|, s98
	v_exp_f32_e32 v145, v145
	v_min_f32_e32 v144, 0, v144
	v_add_f32_e32 v145, 1.0, v145
	v_log_f32_e32 v145, v145
	s_nop 0
	v_fmac_f32_e32 v144, 0xbf317218, v145
	v_cndmask_b32_e64 v144, 0, v144, s[24:25]
	v_add_f32_e32 v159, v159, v144
	v_lshlrev_b32_e32 v144, 16, v67
	v_add_f32_e32 v144, v150, v144
	v_mul_f32_e64 v145, |v144|, s98
	v_exp_f32_e32 v145, v145
	v_min_f32_e32 v144, 0, v144
	v_add_f32_e32 v145, 1.0, v145
	v_log_f32_e32 v145, v145
	s_nop 0
	v_fmac_f32_e32 v144, 0xbf317218, v145
	v_cndmask_b32_e64 v144, 0, v144, s[24:25]
	v_add_f32_e32 v160, v160, v144
	v_and_b32_e32 v144, 0xffff0000, v67
	v_add_f32_e32 v144, v151, v144
	v_mul_f32_e64 v145, |v144|, s98
	v_exp_f32_e32 v145, v145
	v_min_f32_e32 v144, 0, v144
	v_add_f32_e32 v145, 1.0, v145
	v_log_f32_e32 v145, v145
	s_nop 0
	v_fmac_f32_e32 v144, 0xbf317218, v145
	v_cndmask_b32_e64 v144, 0, v144, s[24:25]
	v_add_f32_e32 v161, v161, v144

.Lgn_s7:
	s_cmp_eq_u32 s29, 0x600
	s_cbranch_scc0 .Lglf_s7
	v_add_u32_e32 v146, 56, v147
	v_cmp_le_u32_e64 s[24:25], s36, v146
	v_lshlrev_b32_e32 v144, 16, v64
	v_add_f32_e32 v144, v170, v144
	v_mul_f32_e64 v145, |v144|, s98
	v_exp_f32_e32 v145, v145
	v_min_f32_e32 v144, 0, v144
	v_add_f32_e32 v145, 1.0, v145
	v_log_f32_e32 v145, v145
	s_nop 0
	v_fmac_f32_e32 v144, 0xbf317218, v145
	v_cndmask_b32_e64 v144, 0, v144, s[24:25]
	v_add_f32_e32 v154, v154, v144
	v_and_b32_e32 v144, 0xffff0000, v64
	v_add_f32_e32 v144, v171, v144
	v_mul_f32_e64 v145, |v144|, s98
	v_exp_f32_e32 v145, v145
	v_min_f32_e32 v144, 0, v144
	v_add_f32_e32 v145, 1.0, v145
	v_log_f32_e32 v145, v145
	s_nop 0
	v_fmac_f32_e32 v144, 0xbf317218, v145
	v_cndmask_b32_e64 v144, 0, v144, s[24:25]
	v_add_f32_e32 v155, v155, v144
	v_lshlrev_b32_e32 v144, 16, v65
	v_add_f32_e32 v144, v172, v144
	v_mul_f32_e64 v145, |v144|, s98
	v_exp_f32_e32 v145, v145
	v_min_f32_e32 v144, 0, v144
	v_add_f32_e32 v145, 1.0, v145
	v_log_f32_e32 v145, v145
	s_nop 0
	v_fmac_f32_e32 v144, 0xbf317218, v145
	v_cndmask_b32_e64 v144, 0, v144, s[24:25]
	v_add_f32_e32 v156, v156, v144
	v_and_b32_e32 v144, 0xffff0000, v65
	v_add_f32_e32 v144, v173, v144
	v_mul_f32_e64 v145, |v144|, s98
	v_exp_f32_e32 v145, v145
	v_min_f32_e32 v144, 0, v144
	v_add_f32_e32 v145, 1.0, v145
	v_log_f32_e32 v145, v145
	s_nop 0
	v_fmac_f32_e32 v144, 0xbf317218, v145
	v_cndmask_b32_e64 v144, 0, v144, s[24:25]
	v_add_f32_e32 v157, v157, v144
	v_lshlrev_b32_e32 v144, 16, v66
	v_add_f32_e32 v144, v148, v144
	v_mul_f32_e64 v145, |v144|, s98
	v_exp_f32_e32 v145, v145
	v_min_f32_e32 v144, 0, v144
	v_add_f32_e32 v145, 1.0, v145
	v_log_f32_e32 v145, v145
	s_nop 0
	v_fmac_f32_e32 v144, 0xbf317218, v145
	v_cndmask_b32_e64 v144, 0, v144, s[24:25]
	v_add_f32_e32 v158, v158, v144
	v_and_b32_e32 v144, 0xffff0000, v66
	v_add_f32_e32 v144, v149, v144
	v_mul_f32_e64 v145, |v144|, s98
	v_exp_f32_e32 v145, v145
	v_min_f32_e32 v144, 0, v144
	v_add_f32_e32 v145, 1.0, v145
	v_log_f32_e32 v145, v145
	s_nop 0
	v_fmac_f32_e32 v144, 0xbf317218, v145
	v_cndmask_b32_e64 v144, 0, v144, s[24:25]
	v_add_f32_e32 v159, v159, v144
	v_lshlrev_b32_e32 v144, 16, v67
	v_add_f32_e32 v144, v150, v144
	v_mul_f32_e64 v145, |v144|, s98
	v_exp_f32_e32 v145, v145
	v_min_f32_e32 v144, 0, v144
	v_add_f32_e32 v145, 1.0, v145
	v_log_f32_e32 v145, v145
	s_nop 0
	v_fmac_f32_e32 v144, 0xbf317218, v145
	v_cndmask_b32_e64 v144, 0, v144, s[24:25]
	v_add_f32_e32 v160, v160, v144
	v_and_b32_e32 v144, 0xffff0000, v67
	v_add_f32_e32 v144, v151, v144
	v_mul_f32_e64 v145, |v144|, s98
	v_exp_f32_e32 v145, v145
	v_min_f32_e32 v144, 0, v144
	v_add_f32_e32 v145, 1.0, v145
	v_log_f32_e32 v145, v145
	s_nop 0
	v_fmac_f32_e32 v144, 0xbf317218, v145
	v_cndmask_b32_e64 v144, 0, v144, s[24:25]
	v_add_f32_e32 v161, v161, v144

.Lgn_s8:
	s_cmp_eq_u32 s29, 0x600
	s_cbranch_scc0 .Lglf_s8
	v_add_u32_e32 v146, 64, v147
	v_cmp_le_u32_e64 s[24:25], s36, v146
	v_lshlrev_b32_e32 v144, 16, v32
	v_add_f32_e32 v144, v170, v144
	v_mul_f32_e64 v145, |v144|, s98
	v_exp_f32_e32 v145, v145
	v_min_f32_e32 v144, 0, v144
	v_add_f32_e32 v145, 1.0, v145
	v_log_f32_e32 v145, v145
	s_nop 0
	v_fmac_f32_e32 v144, 0xbf317218, v145
	v_cndmask_b32_e64 v144, 0, v144, s[24:25]
	v_add_f32_e32 v162, v162, v144
	v_and_b32_e32 v144, 0xffff0000, v32
	v_add_f32_e32 v144, v171, v144
	v_mul_f32_e64 v145, |v144|, s98
	v_exp_f32_e32 v145, v145
	v_min_f32_e32 v144, 0, v144
	v_add_f32_e32 v145, 1.0, v145
	v_log_f32_e32 v145, v145
	s_nop 0
	v_fmac_f32_e32 v144, 0xbf317218, v145
	v_cndmask_b32_e64 v144, 0, v144, s[24:25]
	v_add_f32_e32 v163, v163, v144
	v_lshlrev_b32_e32 v144, 16, v33
	v_add_f32_e32 v144, v172, v144
	v_mul_f32_e64 v145, |v144|, s98
	v_exp_f32_e32 v145, v145
	v_min_f32_e32 v144, 0, v144
	v_add_f32_e32 v145, 1.0, v145
	v_log_f32_e32 v145, v145
	s_nop 0
	v_fmac_f32_e32 v144, 0xbf317218, v145
	v_cndmask_b32_e64 v144, 0, v144, s[24:25]
	v_add_f32_e32 v164, v164, v144
	v_and_b32_e32 v144, 0xffff0000, v33
	v_add_f32_e32 v144, v173, v144
	v_mul_f32_e64 v145, |v144|, s98
	v_exp_f32_e32 v145, v145
	v_min_f32_e32 v144, 0, v144
	v_add_f32_e32 v145, 1.0, v145
	v_log_f32_e32 v145, v145
	s_nop 0
	v_fmac_f32_e32 v144, 0xbf317218, v145
	v_cndmask_b32_e64 v144, 0, v144, s[24:25]
	v_add_f32_e32 v165, v165, v144
	v_lshlrev_b32_e32 v144, 16, v34
	v_add_f32_e32 v144, v148, v144
	v_mul_f32_e64 v145, |v144|, s98
	v_exp_f32_e32 v145, v145
	v_min_f32_e32 v144, 0, v144
	v_add_f32_e32 v145, 1.0, v145
	v_log_f32_e32 v145, v145
	s_nop 0
	v_fmac_f32_e32 v144, 0xbf317218, v145
	v_cndmask_b32_e64 v144, 0, v144, s[24:25]
	v_add_f32_e32 v166, v166, v144
	v_and_b32_e32 v144, 0xffff0000, v34
	v_add_f32_e32 v144, v149, v144
	v_mul_f32_e64 v145, |v144|, s98
	v_exp_f32_e32 v145, v145
	v_min_f32_e32 v144, 0, v144
	v_add_f32_e32 v145, 1.0, v145
	v_log_f32_e32 v145, v145
	s_nop 0
	v_fmac_f32_e32 v144, 0xbf317218, v145
	v_cndmask_b32_e64 v144, 0, v144, s[24:25]
	v_add_f32_e32 v167, v167, v144
	v_lshlrev_b32_e32 v144, 16, v35
	v_add_f32_e32 v144, v150, v144
	v_mul_f32_e64 v145, |v144|, s98
	v_exp_f32_e32 v145, v145
	v_min_f32_e32 v144, 0, v144
	v_add_f32_e32 v145, 1.0, v145
	v_log_f32_e32 v145, v145
	s_nop 0
	v_fmac_f32_e32 v144, 0xbf317218, v145
	v_cndmask_b32_e64 v144, 0, v144, s[24:25]
	v_add_f32_e32 v168, v168, v144
	v_and_b32_e32 v144, 0xffff0000, v35
	v_add_f32_e32 v144, v151, v144
	v_mul_f32_e64 v145, |v144|, s98
	v_exp_f32_e32 v145, v145
	v_min_f32_e32 v144, 0, v144
	v_add_f32_e32 v145, 1.0, v145
	v_log_f32_e32 v145, v145
	s_nop 0
	v_fmac_f32_e32 v144, 0xbf317218, v145
	v_cndmask_b32_e64 v144, 0, v144, s[24:25]
	v_add_f32_e32 v169, v169, v144

.Lgn_s9:
	s_cmp_eq_u32 s29, 0x600
	s_cbranch_scc0 .Lglf_s9
	v_add_u32_e32 v146, 72, v147
	v_cmp_le_u32_e64 s[24:25], s36, v146
	v_lshlrev_b32_e32 v144, 16, v32
	v_add_f32_e32 v144, v170, v144
	v_mul_f32_e64 v145, |v144|, s98
	v_exp_f32_e32 v145, v145
	v_min_f32_e32 v144, 0, v144
	v_add_f32_e32 v145, 1.0, v145
	v_log_f32_e32 v145, v145
	s_nop 0
	v_fmac_f32_e32 v144, 0xbf317218, v145
	v_cndmask_b32_e64 v144, 0, v144, s[24:25]
	v_add_f32_e32 v162, v162, v144
	v_and_b32_e32 v144, 0xffff0000, v32
	v_add_f32_e32 v144, v171, v144
	v_mul_f32_e64 v145, |v144|, s98
	v_exp_f32_e32 v145, v145
	v_min_f32_e32 v144, 0, v144
	v_add_f32_e32 v145, 1.0, v145
	v_log_f32_e32 v145, v145
	s_nop 0
	v_fmac_f32_e32 v144, 0xbf317218, v145
	v_cndmask_b32_e64 v144, 0, v144, s[24:25]
	v_add_f32_e32 v163, v163, v144
	v_lshlrev_b32_e32 v144, 16, v33
	v_add_f32_e32 v144, v172, v144
	v_mul_f32_e64 v145, |v144|, s98
	v_exp_f32_e32 v145, v145
	v_min_f32_e32 v144, 0, v144
	v_add_f32_e32 v145, 1.0, v145
	v_log_f32_e32 v145, v145
	s_nop 0
	v_fmac_f32_e32 v144, 0xbf317218, v145
	v_cndmask_b32_e64 v144, 0, v144, s[24:25]
	v_add_f32_e32 v164, v164, v144
	v_and_b32_e32 v144, 0xffff0000, v33
	v_add_f32_e32 v144, v173, v144
	v_mul_f32_e64 v145, |v144|, s98
	v_exp_f32_e32 v145, v145
	v_min_f32_e32 v144, 0, v144
	v_add_f32_e32 v145, 1.0, v145
	v_log_f32_e32 v145, v145
	s_nop 0
	v_fmac_f32_e32 v144, 0xbf317218, v145
	v_cndmask_b32_e64 v144, 0, v144, s[24:25]
	v_add_f32_e32 v165, v165, v144
	v_lshlrev_b32_e32 v144, 16, v34
	v_add_f32_e32 v144, v148, v144
	v_mul_f32_e64 v145, |v144|, s98
	v_exp_f32_e32 v145, v145
	v_min_f32_e32 v144, 0, v144
	v_add_f32_e32 v145, 1.0, v145
	v_log_f32_e32 v145, v145
	s_nop 0
	v_fmac_f32_e32 v144, 0xbf317218, v145
	v_cndmask_b32_e64 v144, 0, v144, s[24:25]
	v_add_f32_e32 v166, v166, v144
	v_and_b32_e32 v144, 0xffff0000, v34
	v_add_f32_e32 v144, v149, v144
	v_mul_f32_e64 v145, |v144|, s98
	v_exp_f32_e32 v145, v145
	v_min_f32_e32 v144, 0, v144
	v_add_f32_e32 v145, 1.0, v145
	v_log_f32_e32 v145, v145
	s_nop 0
	v_fmac_f32_e32 v144, 0xbf317218, v145
	v_cndmask_b32_e64 v144, 0, v144, s[24:25]
	v_add_f32_e32 v167, v167, v144
	v_lshlrev_b32_e32 v144, 16, v35
	v_add_f32_e32 v144, v150, v144
	v_mul_f32_e64 v145, |v144|, s98
	v_exp_f32_e32 v145, v145
	v_min_f32_e32 v144, 0, v144
	v_add_f32_e32 v145, 1.0, v145
	v_log_f32_e32 v145, v145
	s_nop 0
	v_fmac_f32_e32 v144, 0xbf317218, v145
	v_cndmask_b32_e64 v144, 0, v144, s[24:25]
	v_add_f32_e32 v168, v168, v144
	v_and_b32_e32 v144, 0xffff0000, v35
	v_add_f32_e32 v144, v151, v144
	v_mul_f32_e64 v145, |v144|, s98
	v_exp_f32_e32 v145, v145
	v_min_f32_e32 v144, 0, v144
	v_add_f32_e32 v145, 1.0, v145
	v_log_f32_e32 v145, v145
	s_nop 0
	v_fmac_f32_e32 v144, 0xbf317218, v145
	v_cndmask_b32_e64 v144, 0, v144, s[24:25]
	v_add_f32_e32 v169, v169, v144

.Lgn_s10:
	s_cmp_eq_u32 s29, 0x600
	s_cbranch_scc0 .Lglf_s10
	v_add_u32_e32 v146, 80, v147
	v_cmp_le_u32_e64 s[24:25], s36, v146
	v_lshlrev_b32_e32 v144, 16, v32
	v_add_f32_e32 v144, v170, v144
	v_mul_f32_e64 v145, |v144|, s98
	v_exp_f32_e32 v145, v145
	v_min_f32_e32 v144, 0, v144
	v_add_f32_e32 v145, 1.0, v145
	v_log_f32_e32 v145, v145
	s_nop 0
	v_fmac_f32_e32 v144, 0xbf317218, v145
	v_cndmask_b32_e64 v144, 0, v144, s[24:25]
	v_add_f32_e32 v162, v162, v144
	v_and_b32_e32 v144, 0xffff0000, v32
	v_add_f32_e32 v144, v171, v144
	v_mul_f32_e64 v145, |v144|, s98
	v_exp_f32_e32 v145, v145
	v_min_f32_e32 v144, 0, v144
	v_add_f32_e32 v145, 1.0, v145
	v_log_f32_e32 v145, v145
	s_nop 0
	v_fmac_f32_e32 v144, 0xbf317218, v145
	v_cndmask_b32_e64 v144, 0, v144, s[24:25]
	v_add_f32_e32 v163, v163, v144
	v_lshlrev_b32_e32 v144, 16, v33
	v_add_f32_e32 v144, v172, v144
	v_mul_f32_e64 v145, |v144|, s98
	v_exp_f32_e32 v145, v145
	v_min_f32_e32 v144, 0, v144
	v_add_f32_e32 v145, 1.0, v145
	v_log_f32_e32 v145, v145
	s_nop 0
	v_fmac_f32_e32 v144, 0xbf317218, v145
	v_cndmask_b32_e64 v144, 0, v144, s[24:25]
	v_add_f32_e32 v164, v164, v144
	v_and_b32_e32 v144, 0xffff0000, v33
	v_add_f32_e32 v144, v173, v144
	v_mul_f32_e64 v145, |v144|, s98
	v_exp_f32_e32 v145, v145
	v_min_f32_e32 v144, 0, v144
	v_add_f32_e32 v145, 1.0, v145
	v_log_f32_e32 v145, v145
	s_nop 0
	v_fmac_f32_e32 v144, 0xbf317218, v145
	v_cndmask_b32_e64 v144, 0, v144, s[24:25]
	v_add_f32_e32 v165, v165, v144
	v_lshlrev_b32_e32 v144, 16, v34
	v_add_f32_e32 v144, v148, v144
	v_mul_f32_e64 v145, |v144|, s98
	v_exp_f32_e32 v145, v145
	v_min_f32_e32 v144, 0, v144
	v_add_f32_e32 v145, 1.0, v145
	v_log_f32_e32 v145, v145
	s_nop 0
	v_fmac_f32_e32 v144, 0xbf317218, v145
	v_cndmask_b32_e64 v144, 0, v144, s[24:25]
	v_add_f32_e32 v166, v166, v144
	v_and_b32_e32 v144, 0xffff0000, v34
	v_add_f32_e32 v144, v149, v144
	v_mul_f32_e64 v145, |v144|, s98
	v_exp_f32_e32 v145, v145
	v_min_f32_e32 v144, 0, v144
	v_add_f32_e32 v145, 1.0, v145
	v_log_f32_e32 v145, v145
	s_nop 0
	v_fmac_f32_e32 v144, 0xbf317218, v145
	v_cndmask_b32_e64 v144, 0, v144, s[24:25]
	v_add_f32_e32 v167, v167, v144
	v_lshlrev_b32_e32 v144, 16, v35
	v_add_f32_e32 v144, v150, v144
	v_mul_f32_e64 v145, |v144|, s98
	v_exp_f32_e32 v145, v145
	v_min_f32_e32 v144, 0, v144
	v_add_f32_e32 v145, 1.0, v145
	v_log_f32_e32 v145, v145
	s_nop 0
	v_fmac_f32_e32 v144, 0xbf317218, v145
	v_cndmask_b32_e64 v144, 0, v144, s[24:25]
	v_add_f32_e32 v168, v168, v144
	v_and_b32_e32 v144, 0xffff0000, v35
	v_add_f32_e32 v144, v151, v144
	v_mul_f32_e64 v145, |v144|, s98
	v_exp_f32_e32 v145, v145
	v_min_f32_e32 v144, 0, v144
	v_add_f32_e32 v145, 1.0, v145
	v_log_f32_e32 v145, v145
	s_nop 0
	v_fmac_f32_e32 v144, 0xbf317218, v145
	v_cndmask_b32_e64 v144, 0, v144, s[24:25]
	v_add_f32_e32 v169, v169, v144

.Lgn_s11:
	s_cmp_eq_u32 s29, 0x600
	s_cbranch_scc0 .Lglf_s11
	v_add_u32_e32 v146, 88, v147
	v_cmp_le_u32_e64 s[24:25], s36, v146
	v_lshlrev_b32_e32 v144, 16, v32
	v_add_f32_e32 v144, v170, v144
	v_mul_f32_e64 v145, |v144|, s98
	v_exp_f32_e32 v145, v145
	v_min_f32_e32 v144, 0, v144
	v_add_f32_e32 v145, 1.0, v145
	v_log_f32_e32 v145, v145
	s_nop 0
	v_fmac_f32_e32 v144, 0xbf317218, v145
	v_cndmask_b32_e64 v144, 0, v144, s[24:25]
	v_add_f32_e32 v162, v162, v144
	v_and_b32_e32 v144, 0xffff0000, v32
	v_add_f32_e32 v144, v171, v144
	v_mul_f32_e64 v145, |v144|, s98
	v_exp_f32_e32 v145, v145
	v_min_f32_e32 v144, 0, v144
	v_add_f32_e32 v145, 1.0, v145
	v_log_f32_e32 v145, v145
	s_nop 0
	v_fmac_f32_e32 v144, 0xbf317218, v145
	v_cndmask_b32_e64 v144, 0, v144, s[24:25]
	v_add_f32_e32 v163, v163, v144
	v_lshlrev_b32_e32 v144, 16, v33
	v_add_f32_e32 v144, v172, v144
	v_mul_f32_e64 v145, |v144|, s98
	v_exp_f32_e32 v145, v145
	v_min_f32_e32 v144, 0, v144
	v_add_f32_e32 v145, 1.0, v145
	v_log_f32_e32 v145, v145
	s_nop 0
	v_fmac_f32_e32 v144, 0xbf317218, v145
	v_cndmask_b32_e64 v144, 0, v144, s[24:25]
	v_add_f32_e32 v164, v164, v144
	v_and_b32_e32 v144, 0xffff0000, v33
	v_add_f32_e32 v144, v173, v144
	v_mul_f32_e64 v145, |v144|, s98
	v_exp_f32_e32 v145, v145
	v_min_f32_e32 v144, 0, v144
	v_add_f32_e32 v145, 1.0, v145
	v_log_f32_e32 v145, v145
	s_nop 0
	v_fmac_f32_e32 v144, 0xbf317218, v145
	v_cndmask_b32_e64 v144, 0, v144, s[24:25]
	v_add_f32_e32 v165, v165, v144
	v_lshlrev_b32_e32 v144, 16, v34
	v_add_f32_e32 v144, v148, v144
	v_mul_f32_e64 v145, |v144|, s98
	v_exp_f32_e32 v145, v145
	v_min_f32_e32 v144, 0, v144
	v_add_f32_e32 v145, 1.0, v145
	v_log_f32_e32 v145, v145
	s_nop 0
	v_fmac_f32_e32 v144, 0xbf317218, v145
	v_cndmask_b32_e64 v144, 0, v144, s[24:25]
	v_add_f32_e32 v166, v166, v144
	v_and_b32_e32 v144, 0xffff0000, v34
	v_add_f32_e32 v144, v149, v144
	v_mul_f32_e64 v145, |v144|, s98
	v_exp_f32_e32 v145, v145
	v_min_f32_e32 v144, 0, v144
	v_add_f32_e32 v145, 1.0, v145
	v_log_f32_e32 v145, v145
	s_nop 0
	v_fmac_f32_e32 v144, 0xbf317218, v145
	v_cndmask_b32_e64 v144, 0, v144, s[24:25]
	v_add_f32_e32 v167, v167, v144
	v_lshlrev_b32_e32 v144, 16, v35
	v_add_f32_e32 v144, v150, v144
	v_mul_f32_e64 v145, |v144|, s98
	v_exp_f32_e32 v145, v145
	v_min_f32_e32 v144, 0, v144
	v_add_f32_e32 v145, 1.0, v145
	v_log_f32_e32 v145, v145
	s_nop 0
	v_fmac_f32_e32 v144, 0xbf317218, v145
	v_cndmask_b32_e64 v144, 0, v144, s[24:25]
	v_add_f32_e32 v168, v168, v144
	v_and_b32_e32 v144, 0xffff0000, v35
	v_add_f32_e32 v144, v151, v144
	v_mul_f32_e64 v145, |v144|, s98
	v_exp_f32_e32 v145, v145
	v_min_f32_e32 v144, 0, v144
	v_add_f32_e32 v145, 1.0, v145
	v_log_f32_e32 v145, v145
	s_nop 0
	v_fmac_f32_e32 v144, 0xbf317218, v145
	v_cndmask_b32_e64 v144, 0, v144, s[24:25]
	v_add_f32_e32 v169, v169, v144

.Lgn_s12:
	s_cmp_eq_u32 s29, 0x600
	s_cbranch_scc0 .Lglf_s12
	v_add_u32_e32 v146, 96, v147
	v_cmp_le_u32_e64 s[24:25], s36, v146
	v_lshlrev_b32_e32 v144, 16, v0
	v_add_f32_e32 v144, v170, v144
	v_mul_f32_e64 v145, |v144|, s98
	v_exp_f32_e32 v145, v145
	v_min_f32_e32 v144, 0, v144
	v_add_f32_e32 v145, 1.0, v145
	v_log_f32_e32 v145, v145
	s_nop 0
	v_fmac_f32_e32 v144, 0xbf317218, v145
	v_cndmask_b32_e64 v144, 0, v144, s[24:25]
	v_add_f32_e32 v162, v162, v144
	v_and_b32_e32 v144, 0xffff0000, v0
	v_add_f32_e32 v144, v171, v144
	v_mul_f32_e64 v145, |v144|, s98
	v_exp_f32_e32 v145, v145
	v_min_f32_e32 v144, 0, v144
	v_add_f32_e32 v145, 1.0, v145
	v_log_f32_e32 v145, v145
	s_nop 0
	v_fmac_f32_e32 v144, 0xbf317218, v145
	v_cndmask_b32_e64 v144, 0, v144, s[24:25]
	v_add_f32_e32 v163, v163, v144
	v_lshlrev_b32_e32 v144, 16, v1
	v_add_f32_e32 v144, v172, v144
	v_mul_f32_e64 v145, |v144|, s98
	v_exp_f32_e32 v145, v145
	v_min_f32_e32 v144, 0, v144
	v_add_f32_e32 v145, 1.0, v145
	v_log_f32_e32 v145, v145
	s_nop 0
	v_fmac_f32_e32 v144, 0xbf317218, v145
	v_cndmask_b32_e64 v144, 0, v144, s[24:25]
	v_add_f32_e32 v164, v164, v144
	v_and_b32_e32 v144, 0xffff0000, v1
	v_add_f32_e32 v144, v173, v144
	v_mul_f32_e64 v145, |v144|, s98
	v_exp_f32_e32 v145, v145
	v_min_f32_e32 v144, 0, v144
	v_add_f32_e32 v145, 1.0, v145
	v_log_f32_e32 v145, v145
	s_nop 0
	v_fmac_f32_e32 v144, 0xbf317218, v145
	v_cndmask_b32_e64 v144, 0, v144, s[24:25]
	v_add_f32_e32 v165, v165, v144
	v_lshlrev_b32_e32 v144, 16, v2
	v_add_f32_e32 v144, v148, v144
	v_mul_f32_e64 v145, |v144|, s98
	v_exp_f32_e32 v145, v145
	v_min_f32_e32 v144, 0, v144
	v_add_f32_e32 v145, 1.0, v145
	v_log_f32_e32 v145, v145
	s_nop 0
	v_fmac_f32_e32 v144, 0xbf317218, v145
	v_cndmask_b32_e64 v144, 0, v144, s[24:25]
	v_add_f32_e32 v166, v166, v144
	v_and_b32_e32 v144, 0xffff0000, v2
	v_add_f32_e32 v144, v149, v144
	v_mul_f32_e64 v145, |v144|, s98
	v_exp_f32_e32 v145, v145
	v_min_f32_e32 v144, 0, v144
	v_add_f32_e32 v145, 1.0, v145
	v_log_f32_e32 v145, v145
	s_nop 0
	v_fmac_f32_e32 v144, 0xbf317218, v145
	v_cndmask_b32_e64 v144, 0, v144, s[24:25]
	v_add_f32_e32 v167, v167, v144
	v_lshlrev_b32_e32 v144, 16, v3
	v_add_f32_e32 v144, v150, v144
	v_mul_f32_e64 v145, |v144|, s98
	v_exp_f32_e32 v145, v145
	v_min_f32_e32 v144, 0, v144
	v_add_f32_e32 v145, 1.0, v145
	v_log_f32_e32 v145, v145
	s_nop 0
	v_fmac_f32_e32 v144, 0xbf317218, v145
	v_cndmask_b32_e64 v144, 0, v144, s[24:25]
	v_add_f32_e32 v168, v168, v144
	v_and_b32_e32 v144, 0xffff0000, v3
	v_add_f32_e32 v144, v151, v144
	v_mul_f32_e64 v145, |v144|, s98
	v_exp_f32_e32 v145, v145
	v_min_f32_e32 v144, 0, v144
	v_add_f32_e32 v145, 1.0, v145
	v_log_f32_e32 v145, v145
	s_nop 0
	v_fmac_f32_e32 v144, 0xbf317218, v145
	v_cndmask_b32_e64 v144, 0, v144, s[24:25]
	v_add_f32_e32 v169, v169, v144

.Lgn_s13:
	s_cmp_eq_u32 s29, 0x600
	s_cbranch_scc0 .Lglf_s13
	v_add_u32_e32 v146, 104, v147
	v_cmp_le_u32_e64 s[24:25], s36, v146
	v_lshlrev_b32_e32 v144, 16, v0
	v_add_f32_e32 v144, v170, v144
	v_mul_f32_e64 v145, |v144|, s98
	v_exp_f32_e32 v145, v145
	v_min_f32_e32 v144, 0, v144
	v_add_f32_e32 v145, 1.0, v145
	v_log_f32_e32 v145, v145
	s_nop 0
	v_fmac_f32_e32 v144, 0xbf317218, v145
	v_cndmask_b32_e64 v144, 0, v144, s[24:25]
	v_add_f32_e32 v162, v162, v144
	v_and_b32_e32 v144, 0xffff0000, v0
	v_add_f32_e32 v144, v171, v144
	v_mul_f32_e64 v145, |v144|, s98
	v_exp_f32_e32 v145, v145
	v_min_f32_e32 v144, 0, v144
	v_add_f32_e32 v145, 1.0, v145
	v_log_f32_e32 v145, v145
	s_nop 0
	v_fmac_f32_e32 v144, 0xbf317218, v145
	v_cndmask_b32_e64 v144, 0, v144, s[24:25]
	v_add_f32_e32 v163, v163, v144
	v_lshlrev_b32_e32 v144, 16, v1
	v_add_f32_e32 v144, v172, v144
	v_mul_f32_e64 v145, |v144|, s98
	v_exp_f32_e32 v145, v145
	v_min_f32_e32 v144, 0, v144
	v_add_f32_e32 v145, 1.0, v145
	v_log_f32_e32 v145, v145
	s_nop 0
	v_fmac_f32_e32 v144, 0xbf317218, v145
	v_cndmask_b32_e64 v144, 0, v144, s[24:25]
	v_add_f32_e32 v164, v164, v144
	v_and_b32_e32 v144, 0xffff0000, v1
	v_add_f32_e32 v144, v173, v144
	v_mul_f32_e64 v145, |v144|, s98
	v_exp_f32_e32 v145, v145
	v_min_f32_e32 v144, 0, v144
	v_add_f32_e32 v145, 1.0, v145
	v_log_f32_e32 v145, v145
	s_nop 0
	v_fmac_f32_e32 v144, 0xbf317218, v145
	v_cndmask_b32_e64 v144, 0, v144, s[24:25]
	v_add_f32_e32 v165, v165, v144
	v_lshlrev_b32_e32 v144, 16, v2
	v_add_f32_e32 v144, v148, v144
	v_mul_f32_e64 v145, |v144|, s98
	v_exp_f32_e32 v145, v145
	v_min_f32_e32 v144, 0, v144
	v_add_f32_e32 v145, 1.0, v145
	v_log_f32_e32 v145, v145
	s_nop 0
	v_fmac_f32_e32 v144, 0xbf317218, v145
	v_cndmask_b32_e64 v144, 0, v144, s[24:25]
	v_add_f32_e32 v166, v166, v144
	v_and_b32_e32 v144, 0xffff0000, v2
	v_add_f32_e32 v144, v149, v144
	v_mul_f32_e64 v145, |v144|, s98
	v_exp_f32_e32 v145, v145
	v_min_f32_e32 v144, 0, v144
	v_add_f32_e32 v145, 1.0, v145
	v_log_f32_e32 v145, v145
	s_nop 0
	v_fmac_f32_e32 v144, 0xbf317218, v145
	v_cndmask_b32_e64 v144, 0, v144, s[24:25]
	v_add_f32_e32 v167, v167, v144
	v_lshlrev_b32_e32 v144, 16, v3
	v_add_f32_e32 v144, v150, v144
	v_mul_f32_e64 v145, |v144|, s98
	v_exp_f32_e32 v145, v145
	v_min_f32_e32 v144, 0, v144
	v_add_f32_e32 v145, 1.0, v145
	v_log_f32_e32 v145, v145
	s_nop 0
	v_fmac_f32_e32 v144, 0xbf317218, v145
	v_cndmask_b32_e64 v144, 0, v144, s[24:25]
	v_add_f32_e32 v168, v168, v144
	v_and_b32_e32 v144, 0xffff0000, v3
	v_add_f32_e32 v144, v151, v144
	v_mul_f32_e64 v145, |v144|, s98
	v_exp_f32_e32 v145, v145
	v_min_f32_e32 v144, 0, v144
	v_add_f32_e32 v145, 1.0, v145
	v_log_f32_e32 v145, v145
	s_nop 0
	v_fmac_f32_e32 v144, 0xbf317218, v145
	v_cndmask_b32_e64 v144, 0, v144, s[24:25]
	v_add_f32_e32 v169, v169, v144

.Lgn_s14:
	s_cmp_eq_u32 s29, 0x600
	s_cbranch_scc0 .Lglf_s14
	v_add_u32_e32 v146, 112, v147
	v_cmp_le_u32_e64 s[24:25], s36, v146
	v_lshlrev_b32_e32 v144, 16, v0
	v_add_f32_e32 v144, v170, v144
	v_mul_f32_e64 v145, |v144|, s98
	v_exp_f32_e32 v145, v145
	v_min_f32_e32 v144, 0, v144
	v_add_f32_e32 v145, 1.0, v145
	v_log_f32_e32 v145, v145
	s_nop 0
	v_fmac_f32_e32 v144, 0xbf317218, v145
	v_cndmask_b32_e64 v144, 0, v144, s[24:25]
	v_add_f32_e32 v162, v162, v144
	v_and_b32_e32 v144, 0xffff0000, v0
	v_add_f32_e32 v144, v171, v144
	v_mul_f32_e64 v145, |v144|, s98
	v_exp_f32_e32 v145, v145
	v_min_f32_e32 v144, 0, v144
	v_add_f32_e32 v145, 1.0, v145
	v_log_f32_e32 v145, v145
	s_nop 0
	v_fmac_f32_e32 v144, 0xbf317218, v145
	v_cndmask_b32_e64 v144, 0, v144, s[24:25]
	v_add_f32_e32 v163, v163, v144
	v_lshlrev_b32_e32 v144, 16, v1
	v_add_f32_e32 v144, v172, v144
	v_mul_f32_e64 v145, |v144|, s98
	v_exp_f32_e32 v145, v145
	v_min_f32_e32 v144, 0, v144
	v_add_f32_e32 v145, 1.0, v145
	v_log_f32_e32 v145, v145
	s_nop 0
	v_fmac_f32_e32 v144, 0xbf317218, v145
	v_cndmask_b32_e64 v144, 0, v144, s[24:25]
	v_add_f32_e32 v164, v164, v144
	v_and_b32_e32 v144, 0xffff0000, v1
	v_add_f32_e32 v144, v173, v144
	v_mul_f32_e64 v145, |v144|, s98
	v_exp_f32_e32 v145, v145
	v_min_f32_e32 v144, 0, v144
	v_add_f32_e32 v145, 1.0, v145
	v_log_f32_e32 v145, v145
	s_nop 0
	v_fmac_f32_e32 v144, 0xbf317218, v145
	v_cndmask_b32_e64 v144, 0, v144, s[24:25]
	v_add_f32_e32 v165, v165, v144
	v_lshlrev_b32_e32 v144, 16, v2
	v_add_f32_e32 v144, v148, v144
	v_mul_f32_e64 v145, |v144|, s98
	v_exp_f32_e32 v145, v145
	v_min_f32_e32 v144, 0, v144
	v_add_f32_e32 v145, 1.0, v145
	v_log_f32_e32 v145, v145
	s_nop 0
	v_fmac_f32_e32 v144, 0xbf317218, v145
	v_cndmask_b32_e64 v144, 0, v144, s[24:25]
	v_add_f32_e32 v166, v166, v144
	v_and_b32_e32 v144, 0xffff0000, v2
	v_add_f32_e32 v144, v149, v144
	v_mul_f32_e64 v145, |v144|, s98
	v_exp_f32_e32 v145, v145
	v_min_f32_e32 v144, 0, v144
	v_add_f32_e32 v145, 1.0, v145
	v_log_f32_e32 v145, v145
	s_nop 0
	v_fmac_f32_e32 v144, 0xbf317218, v145
	v_cndmask_b32_e64 v144, 0, v144, s[24:25]
	v_add_f32_e32 v167, v167, v144
	v_lshlrev_b32_e32 v144, 16, v3
	v_add_f32_e32 v144, v150, v144
	v_mul_f32_e64 v145, |v144|, s98
	v_exp_f32_e32 v145, v145
	v_min_f32_e32 v144, 0, v144
	v_add_f32_e32 v145, 1.0, v145
	v_log_f32_e32 v145, v145
	s_nop 0
	v_fmac_f32_e32 v144, 0xbf317218, v145
	v_cndmask_b32_e64 v144, 0, v144, s[24:25]
	v_add_f32_e32 v168, v168, v144
	v_and_b32_e32 v144, 0xffff0000, v3
	v_add_f32_e32 v144, v151, v144
	v_mul_f32_e64 v145, |v144|, s98
	v_exp_f32_e32 v145, v145
	v_min_f32_e32 v144, 0, v144
	v_add_f32_e32 v145, 1.0, v145
	v_log_f32_e32 v145, v145
	s_nop 0
	v_fmac_f32_e32 v144, 0xbf317218, v145
	v_cndmask_b32_e64 v144, 0, v144, s[24:25]
	v_add_f32_e32 v169, v169, v144

.Lgn_s15:
	s_cmp_eq_u32 s29, 0x600
	s_cbranch_scc0 .Lglf_s15
	v_add_u32_e32 v146, 120, v147
	v_cmp_le_u32_e64 s[24:25], s36, v146
	v_lshlrev_b32_e32 v144, 16, v0
	v_add_f32_e32 v144, v170, v144
	v_mul_f32_e64 v145, |v144|, s98
	v_exp_f32_e32 v145, v145
	v_min_f32_e32 v144, 0, v144
	v_add_f32_e32 v145, 1.0, v145
	v_log_f32_e32 v145, v145
	s_nop 0
	v_fmac_f32_e32 v144, 0xbf317218, v145
	v_cndmask_b32_e64 v144, 0, v144, s[24:25]
	v_add_f32_e32 v162, v162, v144
	v_and_b32_e32 v144, 0xffff0000, v0
	v_add_f32_e32 v144, v171, v144
	v_mul_f32_e64 v145, |v144|, s98
	v_exp_f32_e32 v145, v145
	v_min_f32_e32 v144, 0, v144
	v_add_f32_e32 v145, 1.0, v145
	v_log_f32_e32 v145, v145
	s_nop 0
	v_fmac_f32_e32 v144, 0xbf317218, v145
	v_cndmask_b32_e64 v144, 0, v144, s[24:25]
	v_add_f32_e32 v163, v163, v144
	v_lshlrev_b32_e32 v144, 16, v1
	v_add_f32_e32 v144, v172, v144
	v_mul_f32_e64 v145, |v144|, s98
	v_exp_f32_e32 v145, v145
	v_min_f32_e32 v144, 0, v144
	v_add_f32_e32 v145, 1.0, v145
	v_log_f32_e32 v145, v145
	s_nop 0
	v_fmac_f32_e32 v144, 0xbf317218, v145
	v_cndmask_b32_e64 v144, 0, v144, s[24:25]
	v_add_f32_e32 v164, v164, v144
	v_and_b32_e32 v144, 0xffff0000, v1
	v_add_f32_e32 v144, v173, v144
	v_mul_f32_e64 v145, |v144|, s98
	v_exp_f32_e32 v145, v145
	v_min_f32_e32 v144, 0, v144
	v_add_f32_e32 v145, 1.0, v145
	v_log_f32_e32 v145, v145
	s_nop 0
	v_fmac_f32_e32 v144, 0xbf317218, v145
	v_cndmask_b32_e64 v144, 0, v144, s[24:25]
	v_add_f32_e32 v165, v165, v144
	v_lshlrev_b32_e32 v144, 16, v2
	v_add_f32_e32 v144, v148, v144
	v_mul_f32_e64 v145, |v144|, s98
	v_exp_f32_e32 v145, v145
	v_min_f32_e32 v144, 0, v144
	v_add_f32_e32 v145, 1.0, v145
	v_log_f32_e32 v145, v145
	s_nop 0
	v_fmac_f32_e32 v144, 0xbf317218, v145
	v_cndmask_b32_e64 v144, 0, v144, s[24:25]
	v_add_f32_e32 v166, v166, v144
	v_and_b32_e32 v144, 0xffff0000, v2
	v_add_f32_e32 v144, v149, v144
	v_mul_f32_e64 v145, |v144|, s98
	v_exp_f32_e32 v145, v145
	v_min_f32_e32 v144, 0, v144
	v_add_f32_e32 v145, 1.0, v145
	v_log_f32_e32 v145, v145
	s_nop 0
	v_fmac_f32_e32 v144, 0xbf317218, v145
	v_cndmask_b32_e64 v144, 0, v144, s[24:25]
	v_add_f32_e32 v167, v167, v144
	v_lshlrev_b32_e32 v144, 16, v3
	v_add_f32_e32 v144, v150, v144
	v_mul_f32_e64 v145, |v144|, s98
	v_exp_f32_e32 v145, v145
	v_min_f32_e32 v144, 0, v144
	v_add_f32_e32 v145, 1.0, v145
	v_log_f32_e32 v145, v145
	s_nop 0
	v_fmac_f32_e32 v144, 0xbf317218, v145
	v_cndmask_b32_e64 v144, 0, v144, s[24:25]
	v_add_f32_e32 v168, v168, v144
	v_and_b32_e32 v144, 0xffff0000, v3
	v_add_f32_e32 v144, v151, v144
	v_mul_f32_e64 v145, |v144|, s98
	v_exp_f32_e32 v145, v145
	v_min_f32_e32 v144, 0, v144
	v_add_f32_e32 v145, 1.0, v145
	v_log_f32_e32 v145, v145
	s_nop 0
	v_fmac_f32_e32 v144, 0xbf317218, v145
	v_cndmask_b32_e64 v144, 0, v144, s[24:25]
	v_add_f32_e32 v169, v169, v144
.Lglf_s15:
	global_store_dwordx4 v[4:5], v[0:3], off offset:1152
	s_cmp_eq_u32 s29, 0x600
	s_cbranch_scc0 .Lglf_done
	v_cmp_eq_u32_e64 s[24:25], 0, v238
	v_readlane_b32 s0, v245, 34
	v_readlane_b32 s1, v245, 35
	v_cndmask_b32_e64 v154, 0, v154, s[24:25]
	v_cndmask_b32_e64 v155, 0, v155, s[24:25]
	v_cndmask_b32_e64 v156, 0, v156, s[24:25]
	v_cndmask_b32_e64 v157, 0, v157, s[24:25]
	v_cndmask_b32_e64 v158, 0, v158, s[24:25]
	v_cndmask_b32_e64 v159, 0, v159, s[24:25]
	v_cndmask_b32_e64 v160, 0, v160, s[24:25]
	v_cndmask_b32_e64 v161, 0, v161, s[24:25]
	v_cndmask_b32_e64 v162, 0, v162, s[24:25]
	v_cndmask_b32_e64 v163, 0, v163, s[24:25]
	v_cndmask_b32_e64 v164, 0, v164, s[24:25]
	v_cndmask_b32_e64 v165, 0, v165, s[24:25]
	v_cndmask_b32_e64 v166, 0, v166, s[24:25]
	v_cndmask_b32_e64 v167, 0, v167, s[24:25]
	v_cndmask_b32_e64 v168, 0, v168, s[24:25]
	v_cndmask_b32_e64 v169, 0, v169, s[24:25]
	s_nop 1
	v_add_f32_dpp v154, v154, v154 quad_perm:[1,0,3,2] row_mask:0xf bank_mask:0xf
	v_add_f32_dpp v155, v155, v155 quad_perm:[1,0,3,2] row_mask:0xf bank_mask:0xf
	v_add_f32_dpp v156, v156, v156 quad_perm:[1,0,3,2] row_mask:0xf bank_mask:0xf
	v_add_f32_dpp v157, v157, v157 quad_perm:[1,0,3,2] row_mask:0xf bank_mask:0xf
	v_add_f32_dpp v158, v158, v158 quad_perm:[1,0,3,2] row_mask:0xf bank_mask:0xf
	v_add_f32_dpp v159, v159, v159 quad_perm:[1,0,3,2] row_mask:0xf bank_mask:0xf
	v_add_f32_dpp v160, v160, v160 quad_perm:[1,0,3,2] row_mask:0xf bank_mask:0xf
	v_add_f32_dpp v161, v161, v161 quad_perm:[1,0,3,2] row_mask:0xf bank_mask:0xf
	v_add_f32_dpp v162, v162, v162 quad_perm:[1,0,3,2] row_mask:0xf bank_mask:0xf
	v_add_f32_dpp v163, v163, v163 quad_perm:[1,0,3,2] row_mask:0xf bank_mask:0xf
	v_add_f32_dpp v164, v164, v164 quad_perm:[1,0,3,2] row_mask:0xf bank_mask:0xf
	v_add_f32_dpp v165, v165, v165 quad_perm:[1,0,3,2] row_mask:0xf bank_mask:0xf
	v_add_f32_dpp v166, v166, v166 quad_perm:[1,0,3,2] row_mask:0xf bank_mask:0xf
	v_add_f32_dpp v167, v167, v167 quad_perm:[1,0,3,2] row_mask:0xf bank_mask:0xf
	v_add_f32_dpp v168, v168, v168 quad_perm:[1,0,3,2] row_mask:0xf bank_mask:0xf
	v_add_f32_dpp v169, v169, v169 quad_perm:[1,0,3,2] row_mask:0xf bank_mask:0xf
	s_nop 1
	v_add_f32_dpp v154, v154, v154 quad_perm:[2,3,0,1] row_mask:0xf bank_mask:0xf
	v_add_f32_dpp v155, v155, v155 quad_perm:[2,3,0,1] row_mask:0xf bank_mask:0xf
	v_add_f32_dpp v156, v156, v156 quad_perm:[2,3,0,1] row_mask:0xf bank_mask:0xf
	v_add_f32_dpp v157, v157, v157 quad_perm:[2,3,0,1] row_mask:0xf bank_mask:0xf
	v_add_f32_dpp v158, v158, v158 quad_perm:[2,3,0,1] row_mask:0xf bank_mask:0xf
	v_add_f32_dpp v159, v159, v159 quad_perm:[2,3,0,1] row_mask:0xf bank_mask:0xf
	v_add_f32_dpp v160, v160, v160 quad_perm:[2,3,0,1] row_mask:0xf bank_mask:0xf
	v_add_f32_dpp v161, v161, v161 quad_perm:[2,3,0,1] row_mask:0xf bank_mask:0xf
	v_add_f32_dpp v162, v162, v162 quad_perm:[2,3,0,1] row_mask:0xf bank_mask:0xf
	v_add_f32_dpp v163, v163, v163 quad_perm:[2,3,0,1] row_mask:0xf bank_mask:0xf
	v_add_f32_dpp v164, v164, v164 quad_perm:[2,3,0,1] row_mask:0xf bank_mask:0xf
	v_add_f32_dpp v165, v165, v165 quad_perm:[2,3,0,1] row_mask:0xf bank_mask:0xf
	v_add_f32_dpp v166, v166, v166 quad_perm:[2,3,0,1] row_mask:0xf bank_mask:0xf
	v_add_f32_dpp v167, v167, v167 quad_perm:[2,3,0,1] row_mask:0xf bank_mask:0xf
	v_add_f32_dpp v168, v168, v168 quad_perm:[2,3,0,1] row_mask:0xf bank_mask:0xf
	v_add_f32_dpp v169, v169, v169 quad_perm:[2,3,0,1] row_mask:0xf bank_mask:0xf
	s_nop 1
	v_add_f32_dpp v154, v154, v154 row_half_mirror row_mask:0xf bank_mask:0xf
	v_add_f32_dpp v155, v155, v155 row_half_mirror row_mask:0xf bank_mask:0xf
	v_add_f32_dpp v156, v156, v156 row_half_mirror row_mask:0xf bank_mask:0xf
	v_add_f32_dpp v157, v157, v157 row_half_mirror row_mask:0xf bank_mask:0xf
	v_add_f32_dpp v158, v158, v158 row_half_mirror row_mask:0xf bank_mask:0xf
	v_add_f32_dpp v159, v159, v159 row_half_mirror row_mask:0xf bank_mask:0xf
	v_add_f32_dpp v160, v160, v160 row_half_mirror row_mask:0xf bank_mask:0xf
	v_add_f32_dpp v161, v161, v161 row_half_mirror row_mask:0xf bank_mask:0xf
	v_add_f32_dpp v162, v162, v162 row_half_mirror row_mask:0xf bank_mask:0xf
	v_add_f32_dpp v163, v163, v163 row_half_mirror row_mask:0xf bank_mask:0xf
	v_add_f32_dpp v164, v164, v164 row_half_mirror row_mask:0xf bank_mask:0xf
	v_add_f32_dpp v165, v165, v165 row_half_mirror row_mask:0xf bank_mask:0xf
	v_add_f32_dpp v166, v166, v166 row_half_mirror row_mask:0xf bank_mask:0xf
	v_add_f32_dpp v167, v167, v167 row_half_mirror row_mask:0xf bank_mask:0xf
	v_add_f32_dpp v168, v168, v168 row_half_mirror row_mask:0xf bank_mask:0xf
	v_add_f32_dpp v169, v169, v169 row_half_mirror row_mask:0xf bank_mask:0xf
	s_nop 1
	v_add_f32_dpp v154, v154, v154 row_ror:8 row_mask:0xf bank_mask:0xf
	v_add_f32_dpp v155, v155, v155 row_ror:8 row_mask:0xf bank_mask:0xf
	v_add_f32_dpp v156, v156, v156 row_ror:8 row_mask:0xf bank_mask:0xf
	v_add_f32_dpp v157, v157, v157 row_ror:8 row_mask:0xf bank_mask:0xf
	v_add_f32_dpp v158, v158, v158 row_ror:8 row_mask:0xf bank_mask:0xf
	v_add_f32_dpp v159, v159, v159 row_ror:8 row_mask:0xf bank_mask:0xf
	v_add_f32_dpp v160, v160, v160 row_ror:8 row_mask:0xf bank_mask:0xf
	v_add_f32_dpp v161, v161, v161 row_ror:8 row_mask:0xf bank_mask:0xf
	v_add_f32_dpp v162, v162, v162 row_ror:8 row_mask:0xf bank_mask:0xf
	v_add_f32_dpp v163, v163, v163 row_ror:8 row_mask:0xf bank_mask:0xf
	v_add_f32_dpp v164, v164, v164 row_ror:8 row_mask:0xf bank_mask:0xf
	v_add_f32_dpp v165, v165, v165 row_ror:8 row_mask:0xf bank_mask:0xf
	v_add_f32_dpp v166, v166, v166 row_ror:8 row_mask:0xf bank_mask:0xf
	v_add_f32_dpp v167, v167, v167 row_ror:8 row_mask:0xf bank_mask:0xf
	v_add_f32_dpp v168, v168, v168 row_ror:8 row_mask:0xf bank_mask:0xf
	v_add_f32_dpp v169, v169, v169 row_ror:8 row_mask:0xf bank_mask:0xf
	s_nop 1
	v_readlane_b32 s24, v154, 16
	v_readlane_b32 s25, v154, 32
	v_readlane_b32 vcc_lo, v154, 48
	s_nop 0
	v_add_f32_e32 v154, s24, v154
	v_add_f32_e32 v154, s25, v154
	v_add_f32_e32 v154, vcc_lo, v154
	v_readlane_b32 s24, v155, 16
	v_readlane_b32 s25, v155, 32
	v_readlane_b32 vcc_lo, v155, 48
	s_nop 0
	v_add_f32_e32 v155, s24, v155
	v_add_f32_e32 v155, s25, v155
	v_add_f32_e32 v155, vcc_lo, v155
	v_readlane_b32 s24, v156, 16
	v_readlane_b32 s25, v156, 32
	v_readlane_b32 vcc_lo, v156, 48
	s_nop 0
	v_add_f32_e32 v156, s24, v156
	v_add_f32_e32 v156, s25, v156
	v_add_f32_e32 v156, vcc_lo, v156
	v_readlane_b32 s24, v157, 16
	v_readlane_b32 s25, v157, 32
	v_readlane_b32 vcc_lo, v157, 48
	s_nop 0
	v_add_f32_e32 v157, s24, v157
	v_add_f32_e32 v157, s25, v157
	v_add_f32_e32 v157, vcc_lo, v157
	v_readlane_b32 s24, v158, 16
	v_readlane_b32 s25, v158, 32
	v_readlane_b32 vcc_lo, v158, 48
	s_nop 0
	v_add_f32_e32 v158, s24, v158
	v_add_f32_e32 v158, s25, v158
	v_add_f32_e32 v158, vcc_lo, v158
	v_readlane_b32 s24, v159, 16
	v_readlane_b32 s25, v159, 32
	v_readlane_b32 vcc_lo, v159, 48
	s_nop 0
	v_add_f32_e32 v159, s24, v159
	v_add_f32_e32 v159, s25, v159
	v_add_f32_e32 v159, vcc_lo, v159
	v_readlane_b32 s24, v160, 16
	v_readlane_b32 s25, v160, 32
	v_readlane_b32 vcc_lo, v160, 48
	s_nop 0
	v_add_f32_e32 v160, s24, v160
	v_add_f32_e32 v160, s25, v160
	v_add_f32_e32 v160, vcc_lo, v160
	v_readlane_b32 s24, v161, 16
	v_readlane_b32 s25, v161, 32
	v_readlane_b32 vcc_lo, v161, 48
	s_nop 0
	v_add_f32_e32 v161, s24, v161
	v_add_f32_e32 v161, s25, v161
	v_add_f32_e32 v161, vcc_lo, v161
	v_readlane_b32 s24, v162, 16
	v_readlane_b32 s25, v162, 32
	v_readlane_b32 vcc_lo, v162, 48
	s_nop 0
	v_add_f32_e32 v162, s24, v162
	v_add_f32_e32 v162, s25, v162
	v_add_f32_e32 v162, vcc_lo, v162
	v_readlane_b32 s24, v163, 16
	v_readlane_b32 s25, v163, 32
	v_readlane_b32 vcc_lo, v163, 48
	s_nop 0
	v_add_f32_e32 v163, s24, v163
	v_add_f32_e32 v163, s25, v163
	v_add_f32_e32 v163, vcc_lo, v163
	v_readlane_b32 s24, v164, 16
	v_readlane_b32 s25, v164, 32
	v_readlane_b32 vcc_lo, v164, 48
	s_nop 0
	v_add_f32_e32 v164, s24, v164
	v_add_f32_e32 v164, s25, v164
	v_add_f32_e32 v164, vcc_lo, v164
	v_readlane_b32 s24, v165, 16
	v_readlane_b32 s25, v165, 32
	v_readlane_b32 vcc_lo, v165, 48
	s_nop 0
	v_add_f32_e32 v165, s24, v165
	v_add_f32_e32 v165, s25, v165
	v_add_f32_e32 v165, vcc_lo, v165
	v_readlane_b32 s24, v166, 16
	v_readlane_b32 s25, v166, 32
	v_readlane_b32 vcc_lo, v166, 48
	s_nop 0
	v_add_f32_e32 v166, s24, v166
	v_add_f32_e32 v166, s25, v166
	v_add_f32_e32 v166, vcc_lo, v166
	v_readlane_b32 s24, v167, 16
	v_readlane_b32 s25, v167, 32
	v_readlane_b32 vcc_lo, v167, 48
	s_nop 0
	v_add_f32_e32 v167, s24, v167
	v_add_f32_e32 v167, s25, v167
	v_add_f32_e32 v167, vcc_lo, v167
	v_readlane_b32 s24, v168, 16
	v_readlane_b32 s25, v168, 32
	v_readlane_b32 vcc_lo, v168, 48
	s_nop 0
	v_add_f32_e32 v168, s24, v168
	v_add_f32_e32 v168, s25, v168
	v_add_f32_e32 v168, vcc_lo, v168
	v_readlane_b32 s24, v169, 16
	v_readlane_b32 s25, v169, 32
	v_readlane_b32 vcc_lo, v169, 48
	s_nop 0
	v_add_f32_e32 v169, s24, v169
	v_add_f32_e32 v169, s25, v169
	v_add_f32_e32 v169, vcc_lo, v169
	v_readfirstlane_b32 s24, v239
	s_nop 1
	s_add_u32 s28, s24, s28
	s_mov_b32 s24, 0
	s_cmp_ge_u32 s28, 0x2080
	s_addc_u32 s24, s24, 0
	s_cmp_ge_u32 s28, 0x4100
	s_addc_u32 s24, s24, 0
	s_cmp_ge_u32 s28, 0x6180
	s_addc_u32 s24, s24, 0
	s_mul_i32 s25, s24, 0x2080
	s_sub_u32 s28, s28, s25
	s_lshr_b32 s28, s28, 6
	s_mul_i32 s24, s24, 0x410
	s_add_u32 s24, s24, s28
	s_lshl_b32 s24, s24, 2
	v_mov_b32_e32 v146, s24
	s_mov_b64 s[24:25], exec
	s_mov_b64 exec, 1
	global_store_dword v146, v154, s[0:1] offset:0
	global_store_dword v146, v162, s[0:1] offset:4
	global_store_dword v146, v155, s[0:1] offset:520
	global_store_dword v146, v163, s[0:1] offset:524
	global_store_dword v146, v156, s[0:1] offset:1040
	global_store_dword v146, v164, s[0:1] offset:1044
	global_store_dword v146, v157, s[0:1] offset:1560
	global_store_dword v146, v165, s[0:1] offset:1564
	global_store_dword v146, v158, s[0:1] offset:2080
	global_store_dword v146, v166, s[0:1] offset:2084
	global_store_dword v146, v159, s[0:1] offset:2600
	global_store_dword v146, v167, s[0:1] offset:2604
	global_store_dword v146, v160, s[0:1] offset:3120
	global_store_dword v146, v168, s[0:1] offset:3124
	global_store_dword v146, v161, s[0:1] offset:3640
	global_store_dword v146, v169, s[0:1] offset:3644
	s_mov_b64 exec, s[24:25]
.Lglf_done:
	s_cmp_lt_u32 s29, 0x400
	s_cbranch_scc0 .Lgn_done
	v_readlane_b32 s0, v245, 38
	v_readlane_b32 s1, v245, 39
	v_max_f32_dpp v144, v152, v152 row_ror:8 row_mask:0xf bank_mask:0xf
	v_max_f32_dpp v145, v153, v153 row_ror:8 row_mask:0xf bank_mask:0xf
	s_nop 0
	v_max_f32_e32 v152, v152, v144
	v_max_f32_e32 v153, v153, v145
	s_nop 1
	v_readlane_b32 s24, v152, 16
	v_readlane_b32 s25, v153, 16
	s_nop 1
	v_max_f32_e32 v144, s24, v152
	v_max_f32_e32 v145, s25, v153
	v_readlane_b32 s24, v152, 32
	v_readlane_b32 s25, v153, 32
	s_nop 1
	v_max_f32_e32 v144, s24, v144
	v_max_f32_e32 v145, s25, v145
	v_readlane_b32 s24, v152, 48
	v_readlane_b32 s25, v153, 48
	s_nop 1
	v_max_f32_e32 v144, s24, v144
	v_max_f32_e32 v145, s25, v145
	v_readfirstlane_b32 s24, v239
	v_readfirstlane_b32 s25, v238
	s_nop 1
	s_add_u32 s28, s24, s28
	s_add_u32 s29, s25, s29
	s_mov_b32 s24, 0
	s_cmp_ge_u32 s28, 0x2080
	s_addc_u32 s24, s24, 0
	s_cmp_ge_u32 s28, 0x4100
	s_addc_u32 s24, s24, 0
	s_cmp_ge_u32 s28, 0x6180
	s_addc_u32 s24, s24, 0
	s_mul_i32 s25, s24, 0x2080
	s_sub_u32 s28, s28, s25
	s_lshr_b32 s28, s28, 6
	s_lshr_b32 s25, s29, 6
	s_and_b32 s25, s25, 7
	s_lshl_b32 s24, s24, 3
	s_add_u32 s24, s24, s25
	s_mul_i32 s24, s24, 0x82
	s_add_u32 s24, s24, s28
	s_lshl_b32 s24, s24, 3
	s_lshr_b32 s29, s29, 9
	s_lshl_b32 s29, s29, 2
	s_add_u32 s24, s24, s29
	v_mov_b32_e32 v146, s24
	s_mov_b64 s[24:25], exec
	s_mov_b64 exec, 1
	global_store_dword v146, v144, s[0:1]
	global_store_dword v146, v145, s[0:1] offset:8
	s_mov_b64 exec, s[24:25]

.LBB0_126:
	s_or_b64 exec, exec, s[0:1]
	v_readlane_b32 s0, v244, 11
	v_readlane_b32 s1, v244, 12
	s_xor_b64 s[0:1], s[0:1], -1
	v_writelane_b32 v244, s0, 22
	s_barrier
	s_nop 0
	v_writelane_b32 v244, s1, 23
	s_mov_b64 s[0:1], exec
	v_readlane_b32 s2, v245, 45
	v_readlane_b32 s3, v245, 46
	s_and_b64 s[2:3], s[0:1], s[2:3]
	s_mov_b64 exec, s[2:3]
	s_branch .LBB0_135
